# ffn-down GEMM: cross-tile prefetch - next tile's first two K-stages issued by LDS-DMA before the last MFMA group and the residual epilogue
# baseline (speedup 1.0000x reference)
; __device__ __forceinline__ size_t wofs(int layer) { return (layer & 1) ? W2_DELTA : (size_t)0; }
; DI int tid_l() { int t = threadIdx.x; asm volatile("" : "+v"(t)); return t; }
; DI int bid_l() { int t = blockIdx.x; asm volatile("" : "+s"(t)); return t; }
; template <int MF, int BK, class Epi>
; DI void gemm_phase_t(char* lds, const GemmDesc g, const Epi epi) {
;   constexpr int BM = MF * 64, LS = BK + 8, CPR = BK / 8, RSTEP = 256 / CPR;
;   constexpr int APT = BM * CPR / 256, BPT = 128 * CPR / 256, STG = (BM + 128) * LS, NKK = BK / 16;
;   u16* sbase = (u16*)lds;
;   const int tid = tid_l(), lane = tid & 63, w = tid >> 6, wm = w >> 1, wn = w & 1, l31 = lane & 31, h = lane >> 5;
;   const int ntn = g.Npad / 128, ntm = g.M / BM, ntiles = ntm * ntn, nk = g.K / BK;
;   const int lr = tid / CPR, lc = tid % CPR;
;   for (int t = bid_l(); t < ntiles; t += gridDim.x) {
;     const int tn = t % ntn, tm = t / ntn;
;     const int m0 = tm * BM, n0 = tn * 128;
;     const u16* Ap = g.A + (size_t)(m0 + lr) * g.lda + lc * 8;
;     const u16* Bp = g.Bt + (size_t)(n0 + lr) * g.ldb + lc * 8;
; DI void run_phase(const Params& p, char* lds, int ph) {
;     ...
;     case 10: if (en(16)) {
;       const EpiResid ep{p.out, (const float*)(ws + OFF_HCTX), p.out, (float*)(ws + OFF_HCTX), modl + 5 * 1024};
;       GemmDesc g{(const u16*)(ws + OFF_ACT), FF, (const u16*)(ws + wofs(layer) + OFF_WDN), FF, TL, 1024, FF};
;       gemm_phase(lds, g, ep);
.LBB0_27:
	v_readlane_b32 s8, v251, 7
	v_readlane_b32 s10, v251, 9
	v_readlane_b32 s6, v253, 30
	s_xor_b64 s[38:39], s[2:3], -1
	s_add_i32 s4, s4, s10
	s_and_b32 s5, s6, 1
	v_readlane_b32 s9, v251, 8
	s_bitcmp1_b32 s6, 0
	s_cselect_b64 s[8:9], -1, 0
	s_cmp_gt_i32 s4, 5
	s_cselect_b64 s[2:3], -1, 0
	v_writelane_b32 v253, s8, 33
	s_and_b64 s[2:3], s[2:3], s[8:9]
	v_cndmask_b32_e64 v2, 0, 1, s[2:3]
	v_writelane_b32 v253, s9, 34
	v_readfirstlane_b32 s2, v2
	s_add_i32 s4, s4, s2
	s_cmp_eq_u32 s5, 0
	s_cselect_b64 s[20:21], -1, 0
	s_lshr_b32 s2, s6, 1
	v_writelane_b32 v253, s2, 35
	s_mul_i32 s2, s6, 0x36000
	s_add_u32 s2, s30, s2
	s_addc_u32 s3, s31, 0
	s_add_u32 s2, s2, 0x800000
	s_addc_u32 s3, s3, 0
	v_writelane_b32 v253, s2, 36
	s_cmp_lt_i32 s4, 5
	v_readlane_b32 s11, v251, 10
	v_writelane_b32 v253, s3, 37
	v_writelane_b32 v253, s4, 38
	s_mov_b64 s[4:5], 0
	v_writelane_b32 v253, s4, 39
	s_mov_b64 s[2:3], -1
	s_nop 0
	v_writelane_b32 v253, s5, 40
	s_cbranch_scc1 .LBB0_359
	v_readlane_b32 s2, v253, 31
	v_readlane_b32 s3, v253, 32
	s_and_b64 s[2:3], s[2:3], exec
	s_mov_b32 s2, 0x8800
	s_cselect_b32 s2, s2, 0x8000
	v_writelane_b32 v253, s2, 41
	s_nop 0
	v_readlane_b32 s2, v253, 38
	s_cmp_gt_i32 s2, 7
	s_cbranch_scc0 .LBB0_47
	s_cmp_gt_i32 s2, 8
	s_cbranch_scc0 .LBB0_48
	s_cmp_gt_i32 s2, 9
	s_mov_b64 s[2:3], -1
	s_cbranch_scc0 .LBB0_284
	v_writelane_b32 v253, s28, 42
	s_nop 1
	v_writelane_b32 v253, s29, 43
	v_writelane_b32 v253, s30, 44
	v_writelane_b32 v253, s31, 45
	v_writelane_b32 v253, s20, 16
	s_nop 1
	v_writelane_b32 v253, s21, 17
	v_writelane_b32 v253, s38, 46
	s_nop 1
	v_writelane_b32 v253, s39, 47
	s_nop 0
	v_readlane_b32 s2, v253, 38
	s_cmp_eq_u32 s2, 10
	s_cbranch_scc0 .LBB0_283
	v_readlane_b32 s2, v253, 36
	s_load_dwordx4 s[20:23], s[50:51], 0x108
	v_readlane_b32 s3, v253, 37
	s_add_u32 s2, s2, 0x5000
	v_readlane_b32 s4, v253, 16
	s_addc_u32 s3, s3, 0
	v_readlane_b32 s5, v253, 17
	s_and_b64 s[4:5], s[4:5], exec
	s_cselect_b32 s48, 0, 0x1c364000
	s_waitcnt lgkmcnt(0)
	s_add_u32 s4, s22, s48
	s_addc_u32 s5, s23, 0
	s_add_u32 s4, s4, 0x214c000
	s_addc_u32 s5, s5, 0
	v_mov_b32_e32 v4, v0
	v_readlane_b32 s6, v251, 0
	s_cmpk_gt_i32 s6, 0x7ff
	s_cbranch_scc1 .LBB0_37
	v_ashrrev_i32_e32 v2, 31, v4
	v_lshrrev_b32_e32 v2, 29, v2
	v_add_u32_e32 v5, v4, v2
	v_ashrrev_i32_e32 v2, 3, v5
	v_and_b32_e32 v5, -8, v5
	v_sub_u32_e32 v5, v4, v5
	v_lshlrev_b32_e32 v6, 3, v5
	v_ashrrev_i32_e32 v7, 31, v6
	v_lshlrev_b64 v[100:101], 1, v[6:7]
	v_lshl_add_u64 v[6:7], s[22:23], 0, v[100:101]
	s_mov_b64 s[8:9], 0x37ac000
	v_bfe_u32 v8, v4, 5, 1
	v_and_b32_e32 v9, 31, v4
	v_and_b32_e32 v10, 64, v4
	v_lshl_add_u64 v[102:103], v[6:7], 0, s[8:9]
	v_and_b32_e32 v6, 0x5f, v4
	v_ashrrev_i32_e32 v4, 1, v4
	s_movk_i32 s7, 0xffc0
	v_and_or_b32 v112, v4, s7, v9
	s_movk_i32 s7, 0x90
	v_mul_lo_u32 v4, v2, s7
	v_lshlrev_b32_e32 v5, 4, v5
	v_lshlrev_b32_e32 v7, 4, v8
	v_lshl_or_b32 v113, v8, 3, v10
	v_add_u32_e32 v8, 0x3600, v4
	v_mul_lo_u32 v9, v112, s7
	v_mul_u32_u24_e32 v6, 0x90, v6
	v_lshl_add_u64 v[104:105], s[4:5], 0, v[100:101]
	v_lshl_add_u64 v[106:107], s[48:49], 0, v[100:101]
	v_add_u32_e32 v114, v5, v4
	v_add_u32_e32 v115, v5, v8
	v_add_u32_e32 v116, v7, v6
	v_add_u32_e32 v117, v7, v9
	v_bfe_u32 v4, v0, 1, 3
	v_bfe_u32 v5, v0, 5, 1
	v_xor_b32_e32 v4, v4, v5
	v_lshlrev_b32_e32 v4, 4, v4
	v_add_u32_e32 v4, 0x100, v4
	v_and_b32_e32 v5, 31, v0
	v_bfe_u32 v6, v0, 7, 1
	v_lshl_or_b32 v6, v6, 6, v5
	v_lshl_add_u32 v114, v6, 7, v4
	v_bfe_u32 v6, v0, 6, 1
	v_lshl_or_b32 v6, v6, 6, v5
	v_lshl_add_u32 v234, v6, 7, v4
	v_add_u32_e32 v234, 0x4000, v234
	v_xor_b32_e32 v115, 0x20, v114
	v_xor_b32_e32 v235, 0x20, v234
	v_xor_b32_e32 v116, 0x40, v114
	v_xor_b32_e32 v236, 0x40, v234
	v_xor_b32_e32 v117, 0x60, v114
	v_xor_b32_e32 v237, 0x60, v234
	v_bfe_u32 v4, v0, 4, 3
	v_and_b32_e32 v5, 7, v0
	v_xor_b32_e32 v4, v4, v5
	v_lshlrev_b32_e32 v4, 4, v4
	v_bfe_u32 v5, v0, 3, 3
	s_movk_i32 s9, 0x1600
	v_mad_u32_u24 v108, v5, s9, v4
	v_add_u32_e32 v109, 0x2c000, v108
	v_add_u32_e32 v110, 0x58000, v108
	v_add_u32_e32 v111, 0x84000, v108
	v_lshrrev_b32_e32 v5, 6, v0
	v_lshlrev_b32_e32 v5, 10, v5
	v_add_u32_e32 v5, 0x100, v5
	s_nop 0
	v_readfirstlane_b32 s100, v5
	s_mov_b32 s11, 0

; template <int MF, int BK, class Epi>
; DI void gemm_phase_t(char* lds, const GemmDesc g, const Epi epi) {
;     ...
;   for (int t = bid_l(); t < ntiles; t += gridDim.x) {
;     const int tn = t % ntn, tm = t / ntn;
;     const int m0 = tm * BM, n0 = tn * 128;
;     const u16* Ap = g.A + (size_t)(m0 + lr) * g.lda + lc * 8;
;     const u16* Bp = g.Bt + (size_t)(n0 + lr) * g.ldb + lc * 8;
;     u32x4 ra[APT], rb[BPT];
; #pragma unroll
;     for (int j = 0; j < APT; ++j) ra[j] = *(const u32x4*)(Ap + (size_t)j * RSTEP * g.lda);
; #pragma unroll
;     for (int j = 0; j < BPT; ++j) rb[j] = *(const u32x4*)(Bp + (size_t)j * RSTEP * g.ldb);
; #pragma unroll
;     for (int j = 0; j < APT; ++j) *(u32x4*)(sbase + (lr + RSTEP * j) * LS + lc * 8) = ra[j];
; #pragma unroll
;     for (int j = 0; j < BPT; ++j) *(u32x4*)(sbase + BM * LS + (lr + RSTEP * j) * LS + lc * 8) = rb[j];
;     if (nk > 1) {
; #pragma unroll
;       for (int j = 0; j < APT; ++j) ra[j] = *(const u32x4*)(Ap + (size_t)j * RSTEP * g.lda + BK);
; #pragma unroll
;       for (int j = 0; j < BPT; ++j) rb[j] = *(const u32x4*)(Bp + (size_t)j * RSTEP * g.ldb + BK);
;     ...
;     for (int kt = 0; kt < nk; ++kt) {
;       __syncthreads();
;       const u16* sA = sbase + (kt & 1) * STG;
;       const u16* sB = sA + BM * LS;
;       if (kt + 1 < nk) {
;         u16* nA = sbase + ((kt + 1) & 1) * STG;
; #pragma unroll
;         for (int j = 0; j < APT; ++j) *(u32x4*)(nA + (lr + RSTEP * j) * LS + lc * 8) = ra[j];
; #pragma unroll
;         for (int j = 0; j < BPT; ++j) *(u32x4*)(nA + BM * LS + (lr + RSTEP * j) * LS + lc * 8) = rb[j];
;         if (kt + 2 < nk) {
; #pragma unroll
;           for (int j = 0; j < APT; ++j) ra[j] = *(const u32x4*)(Ap + (size_t)j * RSTEP * g.lda + (kt + 2) * BK);
; #pragma unroll
;           for (int j = 0; j < BPT; ++j) rb[j] = *(const u32x4*)(Bp + (size_t)j * RSTEP * g.ldb + (kt + 2) * BK);
;         }
;       }
;       bf16x8 af[NKK][MF], bfr[NKK][2];
; #pragma unroll
;       for (int kk = 0; kk < NKK; ++kk) {
; #pragma unroll
;         for (int ni = 0; ni < 2; ++ni) bfr[kk][ni] = *(const bf16x8*)(sB + (wn * 64 + ni * 32 + l31) * LS + kk * 16 + h * 8);
; #pragma unroll
;         for (int mi = 0; mi < MF; ++mi) af[kk][mi] = *(const bf16x8*)(sA + (wm * (MF * 32) + mi * 32 + l31) * LS + kk * 16 + h * 8);
;       }
;       __builtin_amdgcn_sched_barrier(0);
; #pragma unroll
.Lnomap_tl1:
	s_ashr_i32 s7, s98, 31
	s_lshr_b32 s7, s7, 29
	s_add_i32 s7, s98, s7
	s_and_b32 s8, s7, 0x1fffff8
	s_lshl_b32 s7, s7, 4
	s_and_b32 s7, s7, 0xffffff80
	v_add_u32_e32 v58, s7, v2
	s_sub_i32 s8, s98, s8
	s_lshl_b32 s8, s8, 7
	s_cmp_eq_u32 s11, 1
	s_cbranch_scc1 .Lpf_dn_have
	s_movk_i32 s12, 0x1600
	v_mad_i64_i32 v[4:5], s[10:11], v58, s12, v[102:103]
	v_add_u32_e32 v59, s8, v2
	v_mad_i64_i32 v[12:13], s[10:11], v59, s12, v[104:105]
	v_mov_b32_e32 v60, 0
	v_readfirstlane_b32 s12, v4
	v_readfirstlane_b32 s13, v5
	v_readfirstlane_b32 s14, v12
	v_readfirstlane_b32 s15, v13
	s_add_i32 m0, s100, 0x0
	s_nop 0
	global_load_lds_dwordx4 v108, s[12:13]
	s_add_i32 m0, s100, 0x1000
	s_nop 0
	global_load_lds_dwordx4 v109, s[12:13]
	s_add_i32 m0, s100, 0x2000
	s_nop 0
	global_load_lds_dwordx4 v110, s[12:13]
	s_add_i32 m0, s100, 0x3000
	s_nop 0
	global_load_lds_dwordx4 v111, s[12:13]
	s_add_i32 m0, s100, 0x4000
	s_nop 0
	global_load_lds_dwordx4 v108, s[14:15]
	s_add_i32 m0, s100, 0x5000
	s_nop 0
	global_load_lds_dwordx4 v109, s[14:15]
	s_add_i32 m0, s100, 0x6000
	s_nop 0
	global_load_lds_dwordx4 v110, s[14:15]
	s_add_i32 m0, s100, 0x7000
	s_nop 0
	global_load_lds_dwordx4 v111, s[14:15]
	s_add_u32 s12, s12, 0x80
	s_addc_u32 s13, s13, 0
	s_add_u32 s14, s14, 0x80
	s_addc_u32 s15, s15, 0
	s_add_i32 m0, s100, 0x8000
	s_nop 0
	global_load_lds_dwordx4 v108, s[12:13]
	s_add_i32 m0, s100, 0x9000
	s_nop 0
	global_load_lds_dwordx4 v109, s[12:13]
	s_add_i32 m0, s100, 0xa000
	s_nop 0
	global_load_lds_dwordx4 v110, s[12:13]
	s_add_i32 m0, s100, 0xb000
	s_nop 0
	global_load_lds_dwordx4 v111, s[12:13]
	s_add_i32 m0, s100, 0xc000
	s_nop 0
	global_load_lds_dwordx4 v108, s[14:15]
	s_add_i32 m0, s100, 0xd000
	s_nop 0
	global_load_lds_dwordx4 v109, s[14:15]
	s_add_i32 m0, s100, 0xe000
	s_nop 0
	global_load_lds_dwordx4 v110, s[14:15]
	s_add_i32 m0, s100, 0xf000
	s_nop 0
	global_load_lds_dwordx4 v111, s[14:15]
	s_add_u32 s12, s12, 0x80
	s_addc_u32 s13, s13, 0
	s_add_u32 s14, s14, 0x80
	s_addc_u32 s15, s15, 0
.Lpf_dn_have:
	v_mov_b32_e32 v4, 0
	v_mov_b32_e32 v5, 0
	v_mov_b32_e32 v6, 0
	v_mov_b32_e32 v7, 0
	v_mov_b32_e32 v8, 0
	v_mov_b32_e32 v9, 0
	v_mov_b32_e32 v10, 0
	v_mov_b32_e32 v11, 0
	v_mov_b32_e32 v12, 0
	v_mov_b32_e32 v13, 0
	v_mov_b32_e32 v14, 0
	v_mov_b32_e32 v15, 0
	v_mov_b32_e32 v16, 0
	v_mov_b32_e32 v17, 0
	v_mov_b32_e32 v18, 0
	v_mov_b32_e32 v19, 0
	v_mov_b32_e32 v20, 0
	v_mov_b32_e32 v21, 0
	v_mov_b32_e32 v22, 0
	v_mov_b32_e32 v23, 0
	v_mov_b32_e32 v24, 0
	v_mov_b32_e32 v25, 0
	v_mov_b32_e32 v26, 0
	v_mov_b32_e32 v27, 0
	v_mov_b32_e32 v28, 0
	v_mov_b32_e32 v29, 0
	v_mov_b32_e32 v30, 0
	v_mov_b32_e32 v31, 0
	v_mov_b32_e32 v32, 0
	v_mov_b32_e32 v33, 0
	v_mov_b32_e32 v34, 0
	v_mov_b32_e32 v35, 0
	v_mov_b32_e32 v36, 0
	v_mov_b32_e32 v37, 0
	v_mov_b32_e32 v38, 0
	v_mov_b32_e32 v39, 0
	v_mov_b32_e32 v40, 0
	v_mov_b32_e32 v41, 0
	v_mov_b32_e32 v42, 0
	v_mov_b32_e32 v43, 0
	v_mov_b32_e32 v44, 0
	v_mov_b32_e32 v45, 0
	v_mov_b32_e32 v46, 0
	v_mov_b32_e32 v47, 0
	v_mov_b32_e32 v48, 0
	v_mov_b32_e32 v49, 0
	v_mov_b32_e32 v50, 0
	v_mov_b32_e32 v51, 0
	v_mov_b32_e32 v52, 0
	v_mov_b32_e32 v53, 0
	v_mov_b32_e32 v54, 0
	v_mov_b32_e32 v55, 0
	v_mov_b32_e32 v56, 0
	v_mov_b32_e32 v57, 0
	v_mov_b32_e32 v58, 0
	v_mov_b32_e32 v59, 0
	v_mov_b32_e32 v60, 0
	v_mov_b32_e32 v61, 0
	v_mov_b32_e32 v62, 0
	v_mov_b32_e32 v63, 0
	v_mov_b32_e32 v64, 0
	v_mov_b32_e32 v65, 0
	v_mov_b32_e32 v66, 0
	v_mov_b32_e32 v67, 0
	s_waitcnt vmcnt(0)
	s_waitcnt lgkmcnt(0)
	s_barrier
	ds_read_b128 v[68:71], v234
	ds_read_b128 v[72:75], v234 offset:4096
	ds_read_b128 v[76:79], v114
	ds_read_b128 v[80:83], v114 offset:4096
	ds_read_b128 v[84:87], v235
	ds_read_b128 v[88:91], v235 offset:4096
	ds_read_b128 v[92:95], v115
	ds_read_b128 v[96:99], v115 offset:4096
	ds_read_b128 v[118:121], v236
	ds_read_b128 v[122:125], v236 offset:4096
	ds_read_b128 v[126:129], v116
	ds_read_b128 v[130:133], v116 offset:4096
	ds_read_b128 v[134:137], v237
	ds_read_b128 v[138:141], v237 offset:4096
	ds_read_b128 v[142:145], v117
	ds_read_b128 v[146:149], v117 offset:4096
	s_movk_i32 s9, 21
.Ldma_dn_loop:
	s_waitcnt vmcnt(0)
	s_waitcnt lgkmcnt(0)
	s_barrier
	s_add_i32 m0, s100, 0x0
	s_nop 0
	global_load_lds_dwordx4 v108, s[12:13]
	s_add_i32 m0, s100, 0x1000
	s_nop 0
	global_load_lds_dwordx4 v109, s[12:13]
	s_add_i32 m0, s100, 0x2000
	s_nop 0
	global_load_lds_dwordx4 v110, s[12:13]
	s_add_i32 m0, s100, 0x3000
	s_nop 0
	global_load_lds_dwordx4 v111, s[12:13]
	s_add_i32 m0, s100, 0x4000
	s_nop 0
	global_load_lds_dwordx4 v108, s[14:15]
	s_add_i32 m0, s100, 0x5000
	s_nop 0
	global_load_lds_dwordx4 v109, s[14:15]
	s_add_i32 m0, s100, 0x6000
	s_nop 0
	global_load_lds_dwordx4 v110, s[14:15]
	s_add_i32 m0, s100, 0x7000
	s_nop 0
	global_load_lds_dwordx4 v111, s[14:15]
	s_add_u32 s12, s12, 0x80
	s_addc_u32 s13, s13, 0
	s_add_u32 s14, s14, 0x80
	s_addc_u32 s15, s15, 0
	ds_read_b128 v[150:153], v234 offset:32768
	ds_read_b128 v[154:157], v234 offset:36864
	ds_read_b128 v[158:161], v114 offset:32768
	ds_read_b128 v[162:165], v114 offset:36864
	ds_read_b128 v[168:171], v235 offset:32768
	ds_read_b128 v[172:175], v235 offset:36864
	ds_read_b128 v[176:179], v115 offset:32768
	ds_read_b128 v[180:183], v115 offset:36864
	ds_read_b128 v[184:187], v236 offset:32768
	ds_read_b128 v[188:191], v236 offset:36864
	ds_read_b128 v[192:195], v116 offset:32768
	ds_read_b128 v[198:201], v116 offset:36864
	ds_read_b128 v[218:221], v237 offset:32768
	ds_read_b128 v[222:225], v237 offset:36864
	ds_read_b128 v[226:229], v117 offset:32768
	ds_read_b128 v[230:233], v117 offset:36864
	v_mfma_f32_32x32x16_bf16 v[52:67], v[68:71], v[76:79], v[52:67]
	v_mfma_f32_32x32x16_bf16 v[36:51], v[72:75], v[76:79], v[36:51]
	v_mfma_f32_32x32x16_bf16 v[20:35], v[68:71], v[80:83], v[20:35]
	v_mfma_f32_32x32x16_bf16 v[4:19], v[72:75], v[80:83], v[4:19]
	v_mfma_f32_32x32x16_bf16 v[52:67], v[84:87], v[92:95], v[52:67]
	v_mfma_f32_32x32x16_bf16 v[36:51], v[88:91], v[92:95], v[36:51]
	v_mfma_f32_32x32x16_bf16 v[20:35], v[84:87], v[96:99], v[20:35]
	v_mfma_f32_32x32x16_bf16 v[4:19], v[88:91], v[96:99], v[4:19]
	v_mfma_f32_32x32x16_bf16 v[52:67], v[118:121], v[126:129], v[52:67]
	v_mfma_f32_32x32x16_bf16 v[36:51], v[122:125], v[126:129], v[36:51]
	v_mfma_f32_32x32x16_bf16 v[20:35], v[118:121], v[130:133], v[20:35]
	v_mfma_f32_32x32x16_bf16 v[4:19], v[122:125], v[130:133], v[4:19]
	v_mfma_f32_32x32x16_bf16 v[52:67], v[134:137], v[142:145], v[52:67]
	v_mfma_f32_32x32x16_bf16 v[36:51], v[138:141], v[142:145], v[36:51]
	v_mfma_f32_32x32x16_bf16 v[20:35], v[134:137], v[146:149], v[20:35]
	v_mfma_f32_32x32x16_bf16 v[4:19], v[138:141], v[146:149], v[4:19]
	s_waitcnt vmcnt(0)
	s_waitcnt lgkmcnt(0)
	s_barrier
; #define MFMA32(a, b, c) __builtin_amdgcn_mfma_f32_32x32x16_bf16((a), (b), (c), 0, 0, 0)
; DI int bid_l() { int t = blockIdx.x; asm volatile("" : "+s"(t)); return t; }
; template <int MF, int BK, class Epi>
; DI void gemm_phase_t(char* lds, const GemmDesc g, const Epi epi) {
;     ...
;   for (int t = bid_l(); t < ntiles; t += gridDim.x) {
;     const int tn = t % ntn, tm = t / ntn;
;     const int m0 = tm * BM, n0 = tn * 128;
;     const u16* Ap = g.A + (size_t)(m0 + lr) * g.lda + lc * 8;
;     const u16* Bp = g.Bt + (size_t)(n0 + lr) * g.ldb + lc * 8;
;     u32x4 ra[APT], rb[BPT];
; #pragma unroll
;     for (int j = 0; j < APT; ++j) ra[j] = *(const u32x4*)(Ap + (size_t)j * RSTEP * g.lda);
; #pragma unroll
;     for (int j = 0; j < BPT; ++j) rb[j] = *(const u32x4*)(Bp + (size_t)j * RSTEP * g.ldb);
;     ...
;     for (int kt = 0; kt < nk; ++kt) {
;       __syncthreads();
;       const u16* sA = sbase + (kt & 1) * STG;
;       const u16* sB = sA + BM * LS;
;       if (kt + 1 < nk) {
;         u16* nA = sbase + ((kt + 1) & 1) * STG;
; #pragma unroll
;         for (int j = 0; j < APT; ++j) *(u32x4*)(nA + (lr + RSTEP * j) * LS + lc * 8) = ra[j];
; #pragma unroll
;         for (int j = 0; j < BPT; ++j) *(u32x4*)(nA + BM * LS + (lr + RSTEP * j) * LS + lc * 8) = rb[j];
;         if (kt + 2 < nk) {
; #pragma unroll
;           for (int j = 0; j < APT; ++j) ra[j] = *(const u32x4*)(Ap + (size_t)j * RSTEP * g.lda + (kt + 2) * BK);
; #pragma unroll
;           for (int j = 0; j < BPT; ++j) rb[j] = *(const u32x4*)(Bp + (size_t)j * RSTEP * g.ldb + (kt + 2) * BK);
;         }
;       }
;       bf16x8 af[NKK][MF], bfr[NKK][2];
; #pragma unroll
;       for (int kk = 0; kk < NKK; ++kk) {
; #pragma unroll
;         for (int ni = 0; ni < 2; ++ni) bfr[kk][ni] = *(const bf16x8*)(sB + (wn * 64 + ni * 32 + l31) * LS + kk * 16 + h * 8);
; #pragma unroll
;         for (int mi = 0; mi < MF; ++mi) af[kk][mi] = *(const bf16x8*)(sA + (wm * (MF * 32) + mi * 32 + l31) * LS + kk * 16 + h * 8);
;       }
;       __builtin_amdgcn_sched_barrier(0);
; #pragma unroll
;       for (int kk = 0; kk < NKK; ++kk)
; #pragma unroll
;         for (int mi = 0; mi < MF; ++mi)
; #pragma unroll
;           for (int ni = 0; ni < 2; ++ni) acc[mi][ni] = MFMA32(bfr[kk][ni], af[kk][mi], acc[mi][ni]);
	s_add_i32 m0, s100, 0x8000
	s_nop 0
	global_load_lds_dwordx4 v108, s[12:13]
	s_add_i32 m0, s100, 0x9000
	s_nop 0
	global_load_lds_dwordx4 v109, s[12:13]
	s_add_i32 m0, s100, 0xa000
	s_nop 0
	global_load_lds_dwordx4 v110, s[12:13]
	s_add_i32 m0, s100, 0xb000
	s_nop 0
	global_load_lds_dwordx4 v111, s[12:13]
	s_add_i32 m0, s100, 0xc000
	s_nop 0
	global_load_lds_dwordx4 v108, s[14:15]
	s_add_i32 m0, s100, 0xd000
	s_nop 0
	global_load_lds_dwordx4 v109, s[14:15]
	s_add_i32 m0, s100, 0xe000
	s_nop 0
	global_load_lds_dwordx4 v110, s[14:15]
	s_add_i32 m0, s100, 0xf000
	s_nop 0
	global_load_lds_dwordx4 v111, s[14:15]
	s_add_u32 s12, s12, 0x80
	s_addc_u32 s13, s13, 0
	s_add_u32 s14, s14, 0x80
	s_addc_u32 s15, s15, 0
	ds_read_b128 v[68:71], v234
	ds_read_b128 v[72:75], v234 offset:4096
	ds_read_b128 v[76:79], v114
	ds_read_b128 v[80:83], v114 offset:4096
	ds_read_b128 v[84:87], v235
	ds_read_b128 v[88:91], v235 offset:4096
	ds_read_b128 v[92:95], v115
	ds_read_b128 v[96:99], v115 offset:4096
	ds_read_b128 v[118:121], v236
	ds_read_b128 v[122:125], v236 offset:4096
	ds_read_b128 v[126:129], v116
	ds_read_b128 v[130:133], v116 offset:4096
	ds_read_b128 v[134:137], v237
	ds_read_b128 v[138:141], v237 offset:4096
	ds_read_b128 v[142:145], v117
	ds_read_b128 v[146:149], v117 offset:4096
	v_mfma_f32_32x32x16_bf16 v[52:67], v[150:153], v[158:161], v[52:67]
	v_mfma_f32_32x32x16_bf16 v[36:51], v[154:157], v[158:161], v[36:51]
	v_mfma_f32_32x32x16_bf16 v[20:35], v[150:153], v[162:165], v[20:35]
	v_mfma_f32_32x32x16_bf16 v[4:19], v[154:157], v[162:165], v[4:19]
	v_mfma_f32_32x32x16_bf16 v[52:67], v[168:171], v[176:179], v[52:67]
	v_mfma_f32_32x32x16_bf16 v[36:51], v[172:175], v[176:179], v[36:51]
	v_mfma_f32_32x32x16_bf16 v[20:35], v[168:171], v[180:183], v[20:35]
	v_mfma_f32_32x32x16_bf16 v[4:19], v[172:175], v[180:183], v[4:19]
	v_mfma_f32_32x32x16_bf16 v[52:67], v[184:187], v[192:195], v[52:67]
	v_mfma_f32_32x32x16_bf16 v[36:51], v[188:191], v[192:195], v[36:51]
	v_mfma_f32_32x32x16_bf16 v[20:35], v[184:187], v[198:201], v[20:35]
	v_mfma_f32_32x32x16_bf16 v[4:19], v[188:191], v[198:201], v[4:19]
	v_mfma_f32_32x32x16_bf16 v[52:67], v[218:221], v[226:229], v[52:67]
	v_mfma_f32_32x32x16_bf16 v[36:51], v[222:225], v[226:229], v[36:51]
	v_mfma_f32_32x32x16_bf16 v[20:35], v[218:221], v[230:233], v[20:35]
	v_mfma_f32_32x32x16_bf16 v[4:19], v[222:225], v[230:233], v[4:19]
	s_add_i32 s9, s9, -1
	s_cmp_lg_u32 s9, 0
	s_cbranch_scc1 .Ldma_dn_loop
	s_waitcnt vmcnt(0)
	s_waitcnt lgkmcnt(0)
	s_barrier
	ds_read_b128 v[150:153], v234 offset:32768
	ds_read_b128 v[154:157], v234 offset:36864
	ds_read_b128 v[158:161], v114 offset:32768
	ds_read_b128 v[162:165], v114 offset:36864
	ds_read_b128 v[168:171], v235 offset:32768
	ds_read_b128 v[172:175], v235 offset:36864
	ds_read_b128 v[176:179], v115 offset:32768
	ds_read_b128 v[180:183], v115 offset:36864
	ds_read_b128 v[184:187], v236 offset:32768
	ds_read_b128 v[188:191], v236 offset:36864
	ds_read_b128 v[192:195], v116 offset:32768
	ds_read_b128 v[198:201], v116 offset:36864
	ds_read_b128 v[218:221], v237 offset:32768
	ds_read_b128 v[222:225], v237 offset:36864
	ds_read_b128 v[226:229], v117 offset:32768
	ds_read_b128 v[230:233], v117 offset:36864
	v_mfma_f32_32x32x16_bf16 v[52:67], v[68:71], v[76:79], v[52:67]
	v_mfma_f32_32x32x16_bf16 v[36:51], v[72:75], v[76:79], v[36:51]
	v_mfma_f32_32x32x16_bf16 v[20:35], v[68:71], v[80:83], v[20:35]
	v_mfma_f32_32x32x16_bf16 v[4:19], v[72:75], v[80:83], v[4:19]
	v_mfma_f32_32x32x16_bf16 v[52:67], v[84:87], v[92:95], v[52:67]
	v_mfma_f32_32x32x16_bf16 v[36:51], v[88:91], v[92:95], v[36:51]
	v_mfma_f32_32x32x16_bf16 v[20:35], v[84:87], v[96:99], v[20:35]
	v_mfma_f32_32x32x16_bf16 v[4:19], v[88:91], v[96:99], v[4:19]
	v_mfma_f32_32x32x16_bf16 v[52:67], v[118:121], v[126:129], v[52:67]
	v_mfma_f32_32x32x16_bf16 v[36:51], v[122:125], v[126:129], v[36:51]
	v_mfma_f32_32x32x16_bf16 v[20:35], v[118:121], v[130:133], v[20:35]
	v_mfma_f32_32x32x16_bf16 v[4:19], v[122:125], v[130:133], v[4:19]
	v_mfma_f32_32x32x16_bf16 v[52:67], v[134:137], v[142:145], v[52:67]
	v_mfma_f32_32x32x16_bf16 v[36:51], v[138:141], v[142:145], v[36:51]
	v_mfma_f32_32x32x16_bf16 v[20:35], v[134:137], v[146:149], v[20:35]
	v_mfma_f32_32x32x16_bf16 v[4:19], v[138:141], v[146:149], v[4:19]
	s_waitcnt lgkmcnt(0)
	s_barrier
	s_mov_b32 s11, 0
	v_readlane_b32 s9, v252, 40
	s_add_i32 s9, s9, s6
	s_cmpk_gt_i32 s9, 0x7ff
	s_cbranch_scc1 .Lpf_dn_skip
	s_mov_b32 s98, s9
	v_readlane_b32 s99, v252, 40
	s_cmpk_lg_i32 s99, 0x200
	s_cbranch_scc1 .Lpf_dn_nomap
	s_and_b32 s98, s9, 7
	s_lshl_b32 s98, s98, 3
	s_bfe_u32 s99, s9, 0x30006
	s_add_i32 s98, s98, s99
	s_lshr_b32 s99, s9, 9
	s_lshl_b32 s99, s99, 6
	s_add_i32 s98, s98, s99
	s_lshl_b32 s98, s98, 3
	s_bfe_u32 s99, s9, 0x30003
	s_or_b32 s98, s98, s99
; DI int bid_l() { int t = blockIdx.x; asm volatile("" : "+s"(t)); return t; }
; template <int MF, int BK, class Epi>
; DI void gemm_phase_t(char* lds, const GemmDesc g, const Epi epi) {
;     ...
;   for (int t = bid_l(); t < ntiles; t += gridDim.x) {
;     const int tn = t % ntn, tm = t / ntn;
;     const int m0 = tm * BM, n0 = tn * 128;
;     const u16* Ap = g.A + (size_t)(m0 + lr) * g.lda + lc * 8;
;     const u16* Bp = g.Bt + (size_t)(n0 + lr) * g.ldb + lc * 8;
;     u32x4 ra[APT], rb[BPT];
; #pragma unroll
;     for (int j = 0; j < APT; ++j) ra[j] = *(const u32x4*)(Ap + (size_t)j * RSTEP * g.lda);
; #pragma unroll
;     for (int j = 0; j < BPT; ++j) rb[j] = *(const u32x4*)(Bp + (size_t)j * RSTEP * g.ldb);
; #pragma unroll
;     for (int j = 0; j < APT; ++j) *(u32x4*)(sbase + (lr + RSTEP * j) * LS + lc * 8) = ra[j];
; #pragma unroll
;     for (int j = 0; j < BPT; ++j) *(u32x4*)(sbase + BM * LS + (lr + RSTEP * j) * LS + lc * 8) = rb[j];
;     if (nk > 1) {
; #pragma unroll
;       for (int j = 0; j < APT; ++j) ra[j] = *(const u32x4*)(Ap + (size_t)j * RSTEP * g.lda + BK);
; #pragma unroll
;       for (int j = 0; j < BPT; ++j) rb[j] = *(const u32x4*)(Bp + (size_t)j * RSTEP * g.ldb + BK);
.Lpf_dn_nomap:
	s_lshr_b32 s16, s98, 3
	s_lshl_b32 s16, s16, 7
	s_and_b32 s17, s98, 7
	s_lshl_b32 s17, s17, 7
	v_add_u32_e32 v70, s16, v2
	v_mov_b32_e32 v71, 0x1600
	v_mad_i64_i32 v[72:73], s[10:11], v70, v71, v[102:103]
	v_add_u32_e32 v70, s17, v2
	v_mad_i64_i32 v[74:75], s[10:11], v70, v71, v[104:105]
	s_nop 1
	v_readfirstlane_b32 s12, v72
	v_readfirstlane_b32 s13, v73
	v_readfirstlane_b32 s14, v74
	v_readfirstlane_b32 s15, v75
	s_add_i32 m0, s100, 0x0
	s_nop 0
	global_load_lds_dwordx4 v108, s[12:13]
	s_add_i32 m0, s100, 0x1000
	s_nop 0
	global_load_lds_dwordx4 v109, s[12:13]
	s_add_i32 m0, s100, 0x2000
	s_nop 0
	global_load_lds_dwordx4 v110, s[12:13]
	s_add_i32 m0, s100, 0x3000
	s_nop 0
	global_load_lds_dwordx4 v111, s[12:13]
	s_add_i32 m0, s100, 0x4000
	s_nop 0
	global_load_lds_dwordx4 v108, s[14:15]
	s_add_i32 m0, s100, 0x5000
	s_nop 0
	global_load_lds_dwordx4 v109, s[14:15]
	s_add_i32 m0, s100, 0x6000
	s_nop 0
	global_load_lds_dwordx4 v110, s[14:15]
	s_add_i32 m0, s100, 0x7000
	s_nop 0
	global_load_lds_dwordx4 v111, s[14:15]
	s_add_u32 s12, s12, 0x80
	s_addc_u32 s13, s13, 0
	s_add_u32 s14, s14, 0x80
	s_addc_u32 s15, s15, 0
	s_add_i32 m0, s100, 0x8000
	s_nop 0
	global_load_lds_dwordx4 v108, s[12:13]
	s_add_i32 m0, s100, 0x9000
	s_nop 0
	global_load_lds_dwordx4 v109, s[12:13]
	s_add_i32 m0, s100, 0xa000
	s_nop 0
	global_load_lds_dwordx4 v110, s[12:13]
	s_add_i32 m0, s100, 0xb000
	s_nop 0
	global_load_lds_dwordx4 v111, s[12:13]
	s_add_i32 m0, s100, 0xc000
	s_nop 0
	global_load_lds_dwordx4 v108, s[14:15]
	s_add_i32 m0, s100, 0xd000
	s_nop 0
	global_load_lds_dwordx4 v109, s[14:15]
	s_add_i32 m0, s100, 0xe000
	s_nop 0
	global_load_lds_dwordx4 v110, s[14:15]
	s_add_i32 m0, s100, 0xf000
	s_nop 0
	global_load_lds_dwordx4 v111, s[14:15]
	s_add_u32 s12, s12, 0x80
	s_addc_u32 s13, s13, 0
	s_add_u32 s14, s14, 0x80
	s_addc_u32 s15, s15, 0
	s_mov_b32 s11, 1
; #define MFMA32(a, b, c) __builtin_amdgcn_mfma_f32_32x32x16_bf16((a), (b), (c), 0, 0, 0)
; template <int MF, int BK, class Epi>
; DI void gemm_phase_t(char* lds, const GemmDesc g, const Epi epi) {
;     ...
;       for (int kk = 0; kk < NKK; ++kk)
; #pragma unroll
;         for (int mi = 0; mi < MF; ++mi)
; #pragma unroll
;           for (int ni = 0; ni < 2; ++ni) acc[mi][ni] = MFMA32(bfr[kk][ni], af[kk][mi], acc[mi][ni]);
;     }
;     epi(acc, g.mbase + m0 + wm * (MF * 32), n0 + wn * 64, l31, h);
;   template <int MF> DI void operator()(f32x16 (&acc)[MF][2], int mb, int nb, int l31, int h) const {
; #pragma unroll
;     for (int mi = 0; mi < MF; ++mi) {
;       const int row = mb + mi * 32 + l31;
;       const float* gr = gate + (size_t)modrow(row) * 6144;
;       const float* rp = row < TL ? res_lat + (size_t)row * D : res_ctx + (size_t)(row - TL) * D;
;       float* op = row < TL ? out_lat + (size_t)row * D : out_ctx + (size_t)(row - TL) * D;
; #pragma unroll
;       for (int g4 = 0; g4 < 4; ++g4)
; #pragma unroll
;         for (int ni = 0; ni < 2; ++ni) {
;           const int col0 = nb + 16 * g4 + 8 * h + 4 * ni;
;           const float4 gt = *(const float4*)(gr + col0);
;           const float4 rv = *(const float4*)(rp + col0);
;           *(float4*)(op + col0) = make_float4(rv.x + gt.x * acc[mi][ni][4 * g4], rv.y + gt.y * acc[mi][ni][4 * g4 + 1], rv.z + gt.z * acc[mi][ni][4 * g4 + 2], rv.w + gt.w * acc[mi][ni][4 * g4 + 3]);
;         }
;     }
.Lpf_dn_skip:
	v_mfma_f32_32x32x16_bf16 v[52:67], v[150:153], v[158:161], v[52:67]
	v_mfma_f32_32x32x16_bf16 v[36:51], v[154:157], v[158:161], v[36:51]
	v_mfma_f32_32x32x16_bf16 v[20:35], v[150:153], v[162:165], v[20:35]
	v_mfma_f32_32x32x16_bf16 v[4:19], v[154:157], v[162:165], v[4:19]
	v_mfma_f32_32x32x16_bf16 v[52:67], v[168:171], v[176:179], v[52:67]
	v_mfma_f32_32x32x16_bf16 v[36:51], v[172:175], v[176:179], v[36:51]
	v_mfma_f32_32x32x16_bf16 v[20:35], v[168:171], v[180:183], v[20:35]
	v_mfma_f32_32x32x16_bf16 v[4:19], v[172:175], v[180:183], v[4:19]
	v_mfma_f32_32x32x16_bf16 v[52:67], v[184:187], v[192:195], v[52:67]
	v_mfma_f32_32x32x16_bf16 v[36:51], v[188:191], v[192:195], v[36:51]
	v_mfma_f32_32x32x16_bf16 v[20:35], v[184:187], v[198:201], v[20:35]
	v_mfma_f32_32x32x16_bf16 v[4:19], v[188:191], v[198:201], v[4:19]
	v_mfma_f32_32x32x16_bf16 v[52:67], v[218:221], v[226:229], v[52:67]
	v_mfma_f32_32x32x16_bf16 v[36:51], v[222:225], v[226:229], v[36:51]
	v_mfma_f32_32x32x16_bf16 v[20:35], v[218:221], v[230:233], v[20:35]
	v_mfma_f32_32x32x16_bf16 v[4:19], v[222:225], v[230:233], v[4:19]
	v_or_b32_e32 v68, s8, v113
	v_readlane_b32 s8, v252, 40
	s_add_i32 s6, s6, s8
	s_cmpk_gt_i32 s6, 0x7ff
	v_readlane_b32 s9, v252, 41
	v_mov_b32_e32 v88, s21
	v_mov_b32_e32 v89, s22
	v_mov_b32_e32 v90, s20
	v_add_u32_e32 v86, s7, v112
	v_min_i32_e32 v69, 0x8000, v86
	v_ashrrev_i32_e32 v69, 12, v69
	s_mov_b32 s7, 0x8000
	v_mul_hi_i32_i24_e32 v71, 0x6000, v69
	v_mul_i32_i24_e32 v70, 0x6000, v69
	v_cmp_gt_i32_e32 vcc, s7, v86
	v_add_u32_e32 v69, 0xffff8000, v86
	v_ashrrev_i32_e32 v72, 31, v86
	v_cndmask_b32_e32 v73, 0, v72, vcc
	v_cndmask_b32_e32 v72, v69, v86, vcc
	v_mov_b32_e32 v87, s23
	v_ashrrev_i32_e32 v69, 31, v68
	v_lshl_add_u64 v[70:71], s[2:3], 0, v[70:71]
	v_cndmask_b32_e32 v75, v87, v88, vcc
	v_cndmask_b32_e32 v74, v89, v90, vcc
	v_lshlrev_b64 v[72:73], 12, v[72:73]
	v_lshlrev_b64 v[68:69], 2, v[68:69]
	v_lshl_add_u64 v[72:73], v[74:75], 0, v[72:73]
	v_lshl_add_u64 v[84:85], v[72:73], 0, v[68:69]
	s_movk_i32 s7, 0x7fe0
	v_cmp_gt_i32_e32 vcc, s7, v86
	v_lshl_add_u64 v[82:83], v[70:71], 0, v[68:69]
	s_movk_i32 s7, 0x7fe0
	v_cmp_gt_i32_e32 vcc, s7, v86
	v_or_b32_e32 v76, 32, v86
	v_ashrrev_i32_e32 v72, 31, v76
	v_add_u32_e32 v74, 0xffff8020, v86
	v_cndmask_b32_e32 v73, 0, v72, vcc
	v_cndmask_b32_e32 v72, v74, v76, vcc
	v_cndmask_b32_e32 v75, v87, v88, vcc
	v_cndmask_b32_e32 v74, v89, v90, vcc
	v_lshlrev_b64 v[72:73], 12, v[72:73]
	v_lshl_add_u64 v[72:73], v[74:75], 0, v[72:73]
	v_lshl_add_u64 v[80:81], v[72:73], 0, v[68:69]
	global_load_dwordx4 v[118:121], v[82:83], off
	global_load_dwordx4 v[150:153], v[84:85], off
	global_load_dwordx4 v[122:125], v[82:83], off offset:16
	global_load_dwordx4 v[154:157], v[84:85], off offset:16
	global_load_dwordx4 v[126:129], v[82:83], off offset:64
	global_load_dwordx4 v[158:161], v[84:85], off offset:64
	global_load_dwordx4 v[130:133], v[82:83], off offset:80
	global_load_dwordx4 v[162:165], v[84:85], off offset:80
	global_load_dwordx4 v[134:137], v[82:83], off offset:128
	global_load_dwordx4 v[168:171], v[84:85], off offset:128
	global_load_dwordx4 v[138:141], v[82:83], off offset:144
	global_load_dwordx4 v[172:175], v[84:85], off offset:144
	global_load_dwordx4 v[142:145], v[82:83], off offset:192
	global_load_dwordx4 v[176:179], v[84:85], off offset:192
	global_load_dwordx4 v[146:149], v[82:83], off offset:208
	global_load_dwordx4 v[180:183], v[84:85], off offset:208
	global_load_dwordx4 v[184:187], v[80:81], off
	global_load_dwordx4 v[188:191], v[80:81], off offset:16
	global_load_dwordx4 v[192:195], v[80:81], off offset:64
	global_load_dwordx4 v[198:201], v[80:81], off offset:80
	global_load_dwordx4 v[218:221], v[80:81], off offset:128
	global_load_dwordx4 v[222:225], v[80:81], off offset:144
	global_load_dwordx4 v[226:229], v[80:81], off offset:192
	global_load_dwordx4 v[230:233], v[80:81], off offset:208
	s_waitcnt vmcnt(8)
	s_nop 4
	v_fma_f32 v52, v52, v118, v150
	v_fma_f32 v53, v53, v119, v151
	v_fma_f32 v54, v54, v120, v152
	v_fma_f32 v55, v55, v121, v153
	global_store_dwordx4 v[84:85], v[52:55], off
	v_fma_f32 v36, v36, v122, v154
	v_fma_f32 v37, v37, v123, v155
	v_fma_f32 v38, v38, v124, v156
	v_fma_f32 v39, v39, v125, v157
	global_store_dwordx4 v[84:85], v[36:39], off offset:16
	v_fma_f32 v56, v56, v126, v158
	v_fma_f32 v57, v57, v127, v159
	v_fma_f32 v58, v58, v128, v160
	v_fma_f32 v59, v59, v129, v161
	global_store_dwordx4 v[84:85], v[56:59], off offset:64
	v_fma_f32 v40, v40, v130, v162
	v_fma_f32 v41, v41, v131, v163
	v_fma_f32 v42, v42, v132, v164
	v_fma_f32 v43, v43, v133, v165
	global_store_dwordx4 v[84:85], v[40:43], off offset:80
	v_fma_f32 v60, v60, v134, v168
	v_fma_f32 v61, v61, v135, v169
	v_fma_f32 v62, v62, v136, v170
	v_fma_f32 v63, v63, v137, v171
	global_store_dwordx4 v[84:85], v[60:63], off offset:128
	v_fma_f32 v44, v44, v138, v172
	v_fma_f32 v45, v45, v139, v173
	v_fma_f32 v46, v46, v140, v174
	v_fma_f32 v47, v47, v141, v175
	global_store_dwordx4 v[84:85], v[44:47], off offset:144
	v_fma_f32 v64, v64, v142, v176
	v_fma_f32 v65, v65, v143, v177
	v_fma_f32 v66, v66, v144, v178
	v_fma_f32 v67, v67, v145, v179
	global_store_dwordx4 v[84:85], v[64:67], off offset:192
	v_fma_f32 v48, v48, v146, v180
	v_fma_f32 v49, v49, v147, v181
	v_fma_f32 v50, v50, v148, v182
	v_fma_f32 v51, v51, v149, v183
	global_store_dwordx4 v[84:85], v[48:51], off offset:208
	s_waitcnt vmcnt(8)
	v_fma_f32 v20, v20, v118, v184
	v_fma_f32 v21, v21, v119, v185
	v_fma_f32 v22, v22, v120, v186
	v_fma_f32 v23, v23, v121, v187
	global_store_dwordx4 v[80:81], v[20:23], off
	v_fma_f32 v4, v4, v122, v188
	v_fma_f32 v5, v5, v123, v189
	v_fma_f32 v6, v6, v124, v190
	v_fma_f32 v7, v7, v125, v191
	global_store_dwordx4 v[80:81], v[4:7], off offset:16
	v_fma_f32 v24, v24, v126, v192
	v_fma_f32 v25, v25, v127, v193
	v_fma_f32 v26, v26, v128, v194
	v_fma_f32 v27, v27, v129, v195
	global_store_dwordx4 v[80:81], v[24:27], off offset:64
	v_fma_f32 v8, v8, v130, v198
	v_fma_f32 v9, v9, v131, v199
	v_fma_f32 v10, v10, v132, v200
	v_fma_f32 v11, v11, v133, v201
	global_store_dwordx4 v[80:81], v[8:11], off offset:80
	v_fma_f32 v28, v28, v134, v218
	v_fma_f32 v29, v29, v135, v219
	v_fma_f32 v30, v30, v136, v220
	v_fma_f32 v31, v31, v137, v221
	global_store_dwordx4 v[80:81], v[28:31], off offset:128
	v_fma_f32 v12, v12, v138, v222
	v_fma_f32 v13, v13, v139, v223
	v_fma_f32 v14, v14, v140, v224
	v_fma_f32 v15, v15, v141, v225
	global_store_dwordx4 v[80:81], v[12:15], off offset:144
	v_fma_f32 v32, v32, v142, v226
	v_fma_f32 v33, v33, v143, v227
	v_fma_f32 v34, v34, v144, v228
	v_fma_f32 v35, v35, v145, v229
	global_store_dwordx4 v[80:81], v[32:35], off offset:192
	v_fma_f32 v16, v16, v146, v230
	v_fma_f32 v17, v17, v147, v231
	v_fma_f32 v18, v18, v148, v232
	v_fma_f32 v19, v19, v149, v233
	global_store_dwordx4 v[80:81], v[16:19], off offset:208
	s_cbranch_scc0 .LBB0_34
